# v34 + the same software-pipelined far-tile attention loop for the sample group (grp1)
# baseline (speedup 1.0000x reference)
.LBB0_689:
	s_or_b64 exec, exec, s[4:5]
	s_ashr_i32 s40, s82, 3
	s_lshl_b32 s4, s82, 6
	s_ashr_i32 s41, s40, 31
	s_sub_i32 s81, s48, s4
	s_lshl_b32 s83, s79, 23
	s_lshl_b64 s[10:11], s[40:41], 21
	s_add_u32 s4, s92, s10
	s_addc_u32 s5, s93, s11
	s_add_u32 s4, s4, s83
	s_addc_u32 s5, s5, 0
	s_add_u32 s44, s4, 0x4000000
	s_addc_u32 s45, s5, 0
	s_lshl_b32 s80, s81, 7
	s_lshl_b32 s6, s79, 2
	v_and_b32_e32 v154, 31, v153
	v_mov_b32_e32 v0, s6
	s_or_b32 s6, s80, s67
	v_or_b32_e32 v132, s6, v154
	v_ashrrev_i32_e32 v133, 31, v132
	v_readlane_b32 s12, v254, 32
	v_lshlrev_b64 v[2:3], 8, v[132:133]
	v_bfe_u32 v155, v153, 5, 1
	v_readlane_b32 s16, v254, 36
	v_readlane_b32 s17, v254, 37
	v_lshl_add_u64 v[2:3], s[4:5], 0, v[2:3]
	v_bfe_u32 v140, v153, 4, 2
	s_nop 2
	global_load_dword v6, v0, s[16:17] offset:480
	global_load_dword v7, v0, s[16:17] offset:992
	v_lshl_add_u64 v[2:3], v[2:3], 0, s[28:29]
	v_lshlrev_b32_e32 v130, 4, v155
	v_mov_b32_e32 v131, v1
	v_or_b32_e32 v0, s49, v140
	v_lshl_add_u64 v[2:3], v[2:3], 0, v[130:131]
	v_lshlrev_b32_e32 v8, 4, v153
	v_lshlrev_b32_e32 v161, 4, v0
	global_load_dwordx4 v[110:113], v[2:3], off
	global_load_dwordx4 v[106:109], v[2:3], off offset:32
	global_load_dwordx4 v[102:105], v[2:3], off offset:64
	global_load_dwordx4 v[98:101], v[2:3], off offset:96
	v_and_b32_e32 v160, 0xf0, v8
	v_lshlrev_b32_e32 v2, 8, v0
	v_and_b32_e32 v0, 0x70, v161
	v_bitop3_b32 v0, v0, v2, v160 bitop3:0xde
	v_bfe_u32 v2, v153, 2, 3
	s_mov_b32 s6, 0xffffff3
	v_bitop3_b32 v141, v2, s6, v148 bitop3:0xc8
	v_lshrrev_b32_e32 v2, 1, v153
	v_readlane_b32 s18, v254, 38
	s_cmp_lg_u32 0, -1
	v_and_b32_e32 v143, 8, v2
	v_or_b32_e32 v3, s69, v155
	v_and_b32_e32 v159, 48, v8
	s_cselect_b32 s18, 0, 0
	v_or3_b32 v2, v141, v143, s68
	v_lshl_or_b32 v3, v3, 6, v159
	s_add_i32 s7, s70, 0xc000
	v_lshl_or_b32 v2, v2, 8, v3
	s_mov_b32 m0, s7
	v_lshl_add_u64 v[134:135], s[4:5], 0, v[0:1]
	s_mov_b64 s[8:9], 0x4002000
	s_add_i32 s6, s70, 0xe000
	v_mov_b32_e32 v3, v1
	global_load_lds_dwordx4 v0, s[44:45]
	v_lshl_add_u64 v[4:5], v[134:135], 0, s[8:9]
	s_mov_b32 m0, s6
	v_lshl_add_u64 v[136:137], s[4:5], 0, v[2:3]
	s_mov_b64 s[4:5], 0x8000000
	global_load_lds_dwordx4 v[4:5], off
	v_lshl_add_u64 v[2:3], v[136:137], 0, s[4:5]
	s_mov_b32 m0, s70
	s_mov_b64 s[4:5], 0x8002000
	global_load_lds_dwordx4 v[2:3], off
	v_lshl_add_u64 v[2:3], v[136:137], 0, s[4:5]
	s_add_i32 m0, s70, 0x2000
	s_mov_b64 s[4:5], 0x4004000
	global_load_lds_dwordx4 v[2:3], off
	v_lshl_add_u64 v[2:3], v[134:135], 0, s[4:5]
	s_add_i32 m0, s70, 0x10000
	s_mov_b64 s[4:5], 0x4006000
	global_load_lds_dwordx4 v[2:3], off
	v_lshl_add_u64 v[2:3], v[134:135], 0, s[4:5]
	s_add_i32 m0, s70, 0x12000
	s_mov_b64 s[4:5], 0x4008000
	global_load_lds_dwordx4 v[2:3], off
	s_waitcnt vmcnt(0) lgkmcnt(0)
	s_barrier
	v_lshl_add_u64 v[2:3], v[134:135], 0, s[4:5]
	s_add_i32 m0, s70, 0x14000
	s_mov_b64 s[4:5], 0x400a000
	global_load_lds_dwordx4 v[2:3], off
	v_lshl_add_u64 v[2:3], v[134:135], 0, s[4:5]
	s_add_i32 m0, s70, 0x16000
	s_mov_b64 s[4:5], 0x8004000
	global_load_lds_dwordx4 v[2:3], off
	v_lshl_add_u64 v[2:3], v[136:137], 0, s[4:5]
	s_add_i32 m0, s70, 0x4000
	s_mov_b64 s[4:5], 0x8006000
	global_load_lds_dwordx4 v[2:3], off
	v_lshl_add_u64 v[2:3], v[136:137], 0, s[4:5]
	s_add_i32 m0, s70, 0x6000
	v_lshlrev_b32_e32 v4, 6, v153
	global_load_lds_dwordx4 v[2:3], off
	v_lshlrev_b32_e32 v2, 3, v153
	v_and_b32_e32 v3, 0xc0, v8
	v_and_or_b32 v2, v2, 24, v3
	v_lshlrev_b32_e32 v3, 1, v153
	v_and_b32_e32 v3, 32, v3
	v_and_b32_e32 v4, 0x800, v4
	v_or3_b32 v2, v2, v3, v4
	v_lshlrev_b32_e32 v156, 8, v154
	v_lshlrev_b32_e32 v164, 4, v154
	v_and_b32_e32 v131, 63, v153
	s_waitcnt vmcnt(0)
	v_mul_f32_e32 v142, 0x3fb8aa3b, v6
	v_mul_f32_e32 v133, 0x3fb8aa3b, v7
	v_add_u32_e32 v157, s18, v2
	s_mov_b64 s[4:5], -1
	s_and_b64 vcc, exec, s[36:37]
	v_and_b32_e32 v162, 0x70, v164
	v_add_u32_e32 v163, 0, v156
	v_lshlrev_b32_e32 v158, 2, v155
	v_readlane_b32 s13, v254, 33
	v_readlane_b32 s14, v254, 34
	v_readlane_b32 s15, v254, 35
	v_readlane_b32 s19, v254, 39
	v_readlane_b32 s20, v254, 40
	v_readlane_b32 s21, v254, 41
	v_readlane_b32 s22, v254, 42
	v_readlane_b32 s23, v254, 43
	v_readlane_b32 s24, v254, 44
	v_readlane_b32 s25, v254, 45
	v_readlane_b32 s26, v254, 46
	v_readlane_b32 s27, v254, 47
	s_branch .LBB0_722
	v_bitop3_b32 v167, v130, v162, s51 bitop3:0x36
	v_add_u32_e32 v6, v163, v167
	ds_read_b128 v[2:5], v6 offset:49152
	ds_read_b128 v[6:9], v6 offset:57344
	s_movk_i32 s4, 0xa0
	v_bitop3_b32 v168, v130, v162, s4 bitop3:0x36
	v_add_u32_e32 v38, v163, v168
	s_waitcnt lgkmcnt(0)
	v_mfma_f32_32x32x16_bf16 v[18:33], v[2:5], v[110:113], 0
	ds_read_b128 v[34:37], v38 offset:49152
	ds_read_b128 v[38:41], v38 offset:57344
	s_movk_i32 s4, 0xc0
	v_bitop3_b32 v169, v130, v162, s4 bitop3:0x36
	v_add_u32_e32 v42, v163, v169
	s_movk_i32 s4, 0xe0
	v_bitop3_b32 v170, v130, v162, s4 bitop3:0x36
	v_add_u32_e32 v46, v163, v170
	v_mfma_f32_32x32x16_bf16 v[2:17], v[6:9], v[110:113], 0
	s_mov_b64 s[4:5], 0x400c000
	s_mov_b32 m0, s7
	v_sub_u32_e32 v166, v158, v132
	s_waitcnt lgkmcnt(1)
	v_mfma_f32_32x32x16_bf16 v[18:33], v[34:37], v[106:109], v[18:33]
	ds_read_b128 v[34:37], v42 offset:49152
	ds_read_b128 v[42:45], v42 offset:57344
	s_waitcnt lgkmcnt(2)
	v_mfma_f32_32x32x16_bf16 v[2:17], v[38:41], v[106:109], v[2:17]
	ds_read_b128 v[38:41], v46 offset:49152
	ds_read_b128 v[46:49], v46 offset:57344
	s_waitcnt vmcnt(4) lgkmcnt(0)
	s_barrier
	s_waitcnt lgkmcnt(3)
	v_mfma_f32_32x32x16_bf16 v[18:33], v[34:37], v[102:105], v[18:33]
	v_lshl_add_u64 v[34:35], v[134:135], 0, s[4:5]
	s_mov_b64 s[4:5], 0x400e000
	global_load_lds_dwordx4 v[34:35], off
	v_lshl_add_u64 v[34:35], v[134:135], 0, s[4:5]
	s_mov_b32 m0, s6
	s_mov_b64 s[4:5], 0x8008000
	global_load_lds_dwordx4 v[34:35], off
	v_lshl_add_u64 v[34:35], v[136:137], 0, s[4:5]
	s_mov_b32 m0, s76
	s_mov_b64 s[4:5], 0x800a000
	global_load_lds_dwordx4 v[34:35], off
	v_lshl_add_u64 v[34:35], v[136:137], 0, s[4:5]
	s_mov_b32 m0, s77
	s_waitcnt lgkmcnt(0)
	v_mfma_f32_32x32x16_bf16 v[2:17], v[42:45], v[102:105], v[2:17]
	global_load_lds_dwordx4 v[34:35], off
	s_add_i32 s4, s80, 0xd9
	s_cmpk_gt_u32 s4, 0x172
	v_mfma_f32_32x32x16_bf16 v[18:33], v[38:41], v[98:101], v[18:33]
	v_mfma_f32_32x32x16_bf16 v[2:17], v[46:49], v[98:101], v[2:17]
	s_cbranch_scc1 .LBB0_692
	v_mov_b32_e32 v58, v166
	s_add_i32 s4, 0, 0x18800
	v_add_u32_e32 v36, 1, v58
	v_med3_i32 v37, v36, s53, v146
	v_med3_i32 v36, v36, s65, v147
	v_lshl_add_u32 v38, v36, 2, s4
	v_add_u32_e32 v36, 2, v58
	v_med3_i32 v39, v36, s53, v146
	v_med3_i32 v36, v36, s65, v147
	v_lshl_add_u32 v40, v36, 2, s4
	v_add_u32_e32 v36, 3, v58
	v_med3_i32 v34, v58, s53, v146
	v_med3_i32 v35, v58, s65, v147
	v_med3_i32 v41, v36, s53, v146
	v_med3_i32 v36, v36, s65, v147
	v_lshl_add_u32 v34, v34, 2, s4
	v_lshl_add_u32 v35, v35, 2, s4
	v_lshl_add_u32 v37, v37, 2, s4
	v_lshl_add_u32 v39, v39, 2, s4
	v_lshl_add_u32 v41, v41, 2, s4
	v_lshl_add_u32 v42, v36, 2, s4
	ds_read_b32 v34, v34 offset:512
	ds_read_b32 v36, v35 offset:640
	ds_read_b32 v35, v37 offset:512
	ds_read_b32 v37, v38 offset:640
	ds_read_b32 v38, v39 offset:512
	ds_read_b32 v40, v40 offset:640
	ds_read_b32 v39, v41 offset:512
	ds_read_b32 v41, v42 offset:640
	v_add_u32_e32 v42, 8, v58
	v_med3_i32 v43, v42, s53, v146
	v_med3_i32 v42, v42, s65, v147
	v_lshl_add_u32 v44, v42, 2, s4
	v_add_u32_e32 v42, 9, v58
	v_med3_i32 v45, v42, s53, v146
	v_med3_i32 v42, v42, s65, v147
	v_lshl_add_u32 v46, v42, 2, s4
	v_add_u32_e32 v42, 10, v58
	v_med3_i32 v47, v42, s53, v146
	v_med3_i32 v42, v42, s65, v147
	v_lshl_add_u32 v48, v42, 2, s4
	v_add_u32_e32 v42, 11, v58
	v_med3_i32 v49, v42, s53, v146
	v_med3_i32 v42, v42, s65, v147
	v_lshl_add_u32 v43, v43, 2, s4
	v_lshl_add_u32 v45, v45, 2, s4
	v_lshl_add_u32 v47, v47, 2, s4
	v_lshl_add_u32 v49, v49, 2, s4
	v_lshl_add_u32 v50, v42, 2, s4
	ds_read_b32 v42, v43 offset:512
	ds_read_b32 v44, v44 offset:640
	ds_read_b32 v43, v45 offset:512
	ds_read_b32 v45, v46 offset:640
	ds_read_b32 v46, v47 offset:512
	ds_read_b32 v48, v48 offset:640
	ds_read_b32 v47, v49 offset:512
	ds_read_b32 v49, v50 offset:640
	v_add_u32_e32 v50, 16, v58
	v_med3_i32 v51, v50, s53, v146
	v_med3_i32 v50, v50, s65, v147
	v_lshl_add_u32 v52, v50, 2, s4
	v_add_u32_e32 v50, 17, v58
	v_med3_i32 v53, v50, s53, v146
	v_med3_i32 v50, v50, s65, v147
	v_lshl_add_u32 v54, v50, 2, s4
	v_add_u32_e32 v50, 18, v58
	v_med3_i32 v55, v50, s53, v146
	v_med3_i32 v50, v50, s65, v147
	v_lshl_add_u32 v56, v50, 2, s4
	v_add_u32_e32 v50, 19, v58
	v_add_u32_e32 v61, 25, v58
	v_med3_i32 v57, v50, s53, v146
	v_med3_i32 v50, v50, s65, v147
	v_med3_i32 v62, v61, s53, v146
	v_lshl_add_u32 v51, v51, 2, s4
	v_lshl_add_u32 v53, v53, 2, s4
	v_lshl_add_u32 v55, v55, 2, s4
	v_lshl_add_u32 v57, v57, 2, s4
	v_lshl_add_u32 v59, v50, 2, s4
	v_lshl_add_u32 v64, v62, 2, s4
	v_add_u32_e32 v62, 26, v58
	ds_read_b32 v50, v51 offset:512
	ds_read_b32 v52, v52 offset:640
	ds_read_b32 v51, v53 offset:512
	ds_read_b32 v53, v54 offset:640
	ds_read_b32 v54, v55 offset:512
	ds_read_b32 v56, v56 offset:640
	ds_read_b32 v55, v57 offset:512
	ds_read_b32 v57, v59 offset:640
	v_add_u32_e32 v59, 24, v58
	v_med3_i32 v63, v62, s53, v146
	v_med3_i32 v62, v62, s65, v147
	v_add_u32_e32 v58, 27, v58
	v_med3_i32 v60, v59, s53, v146
	v_med3_i32 v59, v59, s65, v147
	v_med3_i32 v61, v61, s65, v147
	v_lshl_add_u32 v66, v62, 2, s4
	v_med3_i32 v62, v58, s53, v146
	v_lshl_add_u32 v60, v60, 2, s4
	v_lshl_add_u32 v59, v59, 2, s4
	v_lshl_add_u32 v61, v61, 2, s4
	v_lshl_add_u32 v63, v63, 2, s4
	v_med3_i32 v58, v58, s65, v147
	v_lshl_add_u32 v65, v62, 2, s4
	v_lshl_add_u32 v67, v58, 2, s4
	ds_read_b32 v58, v60 offset:512
	ds_read_b32 v60, v59 offset:640
	ds_read_b32 v62, v63 offset:512
	ds_read_b32 v63, v65 offset:512
	ds_read_b32 v59, v64 offset:512
	ds_read_b32 v65, v67 offset:640
	ds_read_b32 v64, v66 offset:640
	ds_read_b32 v61, v61 offset:640
	s_waitcnt lgkmcnt(0)
	v_pk_add_f32 v[32:33], v[32:33], v[62:63]
	v_pk_add_f32 v[30:31], v[30:31], v[58:59]
	v_pk_add_f32 v[28:29], v[28:29], v[54:55]
	v_pk_add_f32 v[26:27], v[26:27], v[50:51]
	v_pk_add_f32 v[24:25], v[24:25], v[46:47]
	v_pk_add_f32 v[22:23], v[22:23], v[42:43]
	v_pk_add_f32 v[20:21], v[20:21], v[38:39]
	v_pk_add_f32 v[18:19], v[18:19], v[34:35]
	v_pk_add_f32 v[16:17], v[16:17], v[64:65]
	v_pk_add_f32 v[14:15], v[14:15], v[60:61]
	v_pk_add_f32 v[12:13], v[12:13], v[56:57]
	v_pk_add_f32 v[10:11], v[10:11], v[52:53]
	v_pk_add_f32 v[8:9], v[8:9], v[48:49]
	v_pk_add_f32 v[6:7], v[6:7], v[44:45]
	v_pk_add_f32 v[4:5], v[4:5], v[40:41]
	v_pk_add_f32 v[2:3], v[2:3], v[36:37]

.LBB0_722:
	s_and_b64 vcc, exec, s[4:5]
	s_cbranch_vccz .LBB0_754
	v_bitop3_b32 v164, v130, v164, s64 bitop3:0x78
	v_add_u32_e32 v164, s28, v164
	v_add_u32_e32 v0, v163, v164
	s_nop 7
	ds_read_b128 v[2:5], v0 offset:49152
	ds_read_b128 v[6:9], v0 offset:57344
	v_bitop3_b32 v165, v130, v162, 32 bitop3:0x36
	v_add_u32_e32 v165, s28, v165
	v_add_u32_e32 v0, v163, v165
	ds_read_b128 v[34:37], v0 offset:49152
	ds_read_b128 v[38:41], v0 offset:57344
	s_waitcnt lgkmcnt(0)
	v_mfma_f32_32x32x16_bf16 v[18:33], v[2:5], v[110:113], 0
	v_bitop3_b32 v166, v130, v162, 64 bitop3:0x36
	v_add_u32_e32 v166, s28, v166
	v_add_u32_e32 v0, v163, v166
	s_movk_i32 s4, 0x60
	v_bitop3_b32 v167, v130, v162, s4 bitop3:0x36
	v_add_u32_e32 v167, s28, v167
	s_add_i32 s4, s80, 0xd9
	s_cmpk_gt_u32 s4, 0x172
	v_mfma_f32_32x32x16_bf16 v[2:17], v[6:9], v[110:113], 0
	v_mfma_f32_32x32x16_bf16 v[18:33], v[34:37], v[106:109], v[18:33]
	v_mfma_f32_32x32x16_bf16 v[2:17], v[38:41], v[106:109], v[2:17]
	ds_read_b128 v[34:37], v0 offset:49152
	ds_read_b128 v[38:41], v0 offset:57344
	v_add_u32_e32 v0, v163, v167
	s_waitcnt lgkmcnt(0)
	v_mfma_f32_32x32x16_bf16 v[18:33], v[34:37], v[102:105], v[18:33]
	v_mfma_f32_32x32x16_bf16 v[2:17], v[38:41], v[102:105], v[2:17]
	ds_read_b128 v[34:37], v0 offset:49152
	ds_read_b128 v[38:41], v0 offset:57344
	s_waitcnt lgkmcnt(0)
	v_mfma_f32_32x32x16_bf16 v[18:33], v[34:37], v[98:101], v[18:33]
	v_mfma_f32_32x32x16_bf16 v[2:17], v[38:41], v[98:101], v[2:17]
	s_cbranch_scc1 .LBB0_725
	v_sub_u32_e32 v0, v158, v132
	s_add_i32 s4, 0, 0x18800
	v_add_u32_e32 v36, 1, v0
	v_med3_i32 v37, v36, s53, v146
	v_med3_i32 v36, v36, s65, v147
	v_lshl_add_u32 v38, v36, 2, s4
	v_add_u32_e32 v36, 2, v0
	v_med3_i32 v39, v36, s53, v146
	v_med3_i32 v36, v36, s65, v147
	v_lshl_add_u32 v40, v36, 2, s4
	v_add_u32_e32 v36, 3, v0
	v_med3_i32 v34, v0, s53, v146
	v_med3_i32 v35, v0, s65, v147
	v_med3_i32 v41, v36, s53, v146
	v_med3_i32 v36, v36, s65, v147
	v_lshl_add_u32 v34, v34, 2, s4
	v_lshl_add_u32 v35, v35, 2, s4
	v_lshl_add_u32 v37, v37, 2, s4
	v_lshl_add_u32 v39, v39, 2, s4
	v_lshl_add_u32 v41, v41, 2, s4
	v_lshl_add_u32 v42, v36, 2, s4
	ds_read_b32 v34, v34 offset:512
	ds_read_b32 v36, v35 offset:640
	ds_read_b32 v35, v37 offset:512
	ds_read_b32 v37, v38 offset:640
	ds_read_b32 v38, v39 offset:512
	ds_read_b32 v40, v40 offset:640
	ds_read_b32 v39, v41 offset:512
	ds_read_b32 v41, v42 offset:640
	v_add_u32_e32 v42, 8, v0
	v_med3_i32 v43, v42, s53, v146
	v_med3_i32 v42, v42, s65, v147
	v_lshl_add_u32 v44, v42, 2, s4
	v_add_u32_e32 v42, 9, v0
	v_med3_i32 v45, v42, s53, v146
	v_med3_i32 v42, v42, s65, v147
	v_lshl_add_u32 v46, v42, 2, s4
	v_add_u32_e32 v42, 10, v0
	v_med3_i32 v47, v42, s53, v146
	v_med3_i32 v42, v42, s65, v147
	v_lshl_add_u32 v48, v42, 2, s4
	v_add_u32_e32 v42, 11, v0
	v_med3_i32 v49, v42, s53, v146
	v_med3_i32 v42, v42, s65, v147
	v_lshl_add_u32 v43, v43, 2, s4
	v_lshl_add_u32 v45, v45, 2, s4
	v_lshl_add_u32 v47, v47, 2, s4
	v_lshl_add_u32 v49, v49, 2, s4
	v_lshl_add_u32 v50, v42, 2, s4
	ds_read_b32 v42, v43 offset:512
	ds_read_b32 v44, v44 offset:640
	ds_read_b32 v43, v45 offset:512
	ds_read_b32 v45, v46 offset:640
	ds_read_b32 v46, v47 offset:512
	ds_read_b32 v48, v48 offset:640
	ds_read_b32 v47, v49 offset:512
	ds_read_b32 v49, v50 offset:640
	v_add_u32_e32 v50, 16, v0
	v_med3_i32 v51, v50, s53, v146
	v_med3_i32 v50, v50, s65, v147
	v_lshl_add_u32 v52, v50, 2, s4
	v_add_u32_e32 v50, 17, v0
	v_med3_i32 v53, v50, s53, v146
	v_med3_i32 v50, v50, s65, v147
	v_lshl_add_u32 v54, v50, 2, s4
	v_add_u32_e32 v50, 18, v0
	v_med3_i32 v55, v50, s53, v146
	v_med3_i32 v50, v50, s65, v147
	v_lshl_add_u32 v56, v50, 2, s4
	v_add_u32_e32 v50, 19, v0
	v_med3_i32 v57, v50, s53, v146
	v_med3_i32 v50, v50, s65, v147
	v_lshl_add_u32 v51, v51, 2, s4
	v_lshl_add_u32 v53, v53, 2, s4
	v_lshl_add_u32 v55, v55, 2, s4
	v_lshl_add_u32 v57, v57, 2, s4
	v_lshl_add_u32 v58, v50, 2, s4
	ds_read_b32 v50, v51 offset:512
	ds_read_b32 v52, v52 offset:640
	ds_read_b32 v51, v53 offset:512
	ds_read_b32 v53, v54 offset:640
	ds_read_b32 v54, v55 offset:512
	ds_read_b32 v56, v56 offset:640
	ds_read_b32 v55, v57 offset:512
	ds_read_b32 v57, v58 offset:640
	v_add_u32_e32 v58, 24, v0
	v_med3_i32 v59, v58, s53, v146
	v_med3_i32 v58, v58, s65, v147
	v_lshl_add_u32 v60, v58, 2, s4
	v_add_u32_e32 v58, 25, v0
	v_med3_i32 v61, v58, s53, v146
	v_med3_i32 v58, v58, s65, v147
	v_lshl_add_u32 v66, v58, 2, s4
	v_add_u32_e32 v58, 26, v0
	v_med3_i32 v62, v58, s53, v146
	v_med3_i32 v58, v58, s65, v147
	v_add_u32_e32 v0, 27, v0
	v_lshl_add_u32 v64, v58, 2, s4
	v_med3_i32 v58, v0, s53, v146
	v_lshl_add_u32 v59, v59, 2, s4
	v_lshl_add_u32 v61, v61, 2, s4
	v_lshl_add_u32 v62, v62, 2, s4
	v_med3_i32 v0, v0, s65, v147
	v_lshl_add_u32 v63, v58, 2, s4
	v_lshl_add_u32 v0, v0, 2, s4
	ds_read_b32 v58, v59 offset:512
	ds_read_b32 v60, v60 offset:640
	ds_read_b32 v62, v62 offset:512
	ds_read_b32 v63, v63 offset:512
	ds_read_b32 v59, v61 offset:512
	ds_read_b32 v65, v0 offset:640
	ds_read_b32 v64, v64 offset:640
	ds_read_b32 v61, v66 offset:640
	s_waitcnt lgkmcnt(0)
	v_pk_add_f32 v[32:33], v[32:33], v[62:63]
	v_pk_add_f32 v[30:31], v[30:31], v[58:59]
	v_pk_add_f32 v[28:29], v[28:29], v[54:55]
	v_pk_add_f32 v[26:27], v[26:27], v[50:51]
	v_pk_add_f32 v[24:25], v[24:25], v[46:47]
	v_pk_add_f32 v[22:23], v[22:23], v[42:43]
	v_pk_add_f32 v[20:21], v[20:21], v[38:39]
	v_pk_add_f32 v[18:19], v[18:19], v[34:35]
	v_pk_add_f32 v[16:17], v[16:17], v[64:65]
	v_pk_add_f32 v[14:15], v[14:15], v[60:61]
	v_pk_add_f32 v[12:13], v[12:13], v[56:57]
	v_pk_add_f32 v[10:11], v[10:11], v[52:53]
	v_pk_add_f32 v[8:9], v[8:9], v[48:49]
	v_pk_add_f32 v[6:7], v[6:7], v[44:45]
	v_pk_add_f32 v[4:5], v[4:5], v[40:41]
	v_pk_add_f32 v[2:3], v[2:3], v[36:37]

.LBB0_730:
	s_add_i32 s10, s86, s87
	s_abs_i32 s11, s10
	s_cmpk_lt_i32 s11, 0xda
	s_cbranch_scc1 .Lfa1_nofast
	s_add_i32 s11, s87, 64
	s_cmpk_eq_i32 s11, 0x1f40
	s_cbranch_scc0 .Lfa1_entry

.Lfa1_entry:
	s_lshl_b32 s10, s83, 14
	s_add_i32 s10, s10, 0xc000
	v_add_u32_e32 v208, s10, v156
	v_add_u32_e32 v252, v208, v164
	ds_read_b128 v[220:223], v252
	v_add_u32_e32 v252, v208, v165
	ds_read_b128 v[224:227], v252
	v_add_u32_e32 v252, v208, v166
	ds_read_b128 v[228:231], v252
	v_add_u32_e32 v252, v208, v167
	ds_read_b128 v[232:235], v252
	v_add_u32_e32 v252, v208, v164
	ds_read_b128 v[236:239], v252 offset:8192
	v_add_u32_e32 v252, v208, v165
	ds_read_b128 v[240:243], v252 offset:8192
	v_add_u32_e32 v252, v208, v166
	ds_read_b128 v[244:247], v252 offset:8192
	v_add_u32_e32 v252, v208, v167
	ds_read_b128 v[248:251], v252 offset:8192
	s_lshl_b32 s10, s6, 14
	v_add_u32_e32 v209, s10, v157
	ds_read_b64_tr_b16 v[168:169], v209 offset:0
	ds_read_b64_tr_b16 v[170:171], v209 offset:256
	ds_read_b64_tr_b16 v[172:173], v209 offset:512
	ds_read_b64_tr_b16 v[174:175], v209 offset:768
	ds_read_b64_tr_b16 v[176:177], v209 offset:1024
	ds_read_b64_tr_b16 v[178:179], v209 offset:1280
	ds_read_b64_tr_b16 v[180:181], v209 offset:1536
	ds_read_b64_tr_b16 v[182:183], v209 offset:1792
	ds_read_b64_tr_b16 v[184:185], v209 offset:4096
	ds_read_b64_tr_b16 v[186:187], v209 offset:4352
	ds_read_b64_tr_b16 v[188:189], v209 offset:4608
	ds_read_b64_tr_b16 v[190:191], v209 offset:4864
	ds_read_b64_tr_b16 v[192:193], v209 offset:5120
	ds_read_b64_tr_b16 v[194:195], v209 offset:5376
	ds_read_b64_tr_b16 v[200:201], v209 offset:5632
	ds_read_b64_tr_b16 v[202:203], v209 offset:5888
	s_waitcnt lgkmcnt(0)
.Lfa1x_loop:
	s_mov_b32 s33, s6
	s_lshl_b32 s8, s33, 14
	v_add_u32_e32 v209, s8, v157
	s_lshl_b32 s10, s83, 14
	v_add_u32_e32 v210, s10, v157
	s_lshl_b32 s46, s84, 14
	s_add_i32 s10, s46, 0xc000
	v_add_u32_e32 v208, s10, v156
	s_waitcnt lgkmcnt(15)
	v_mfma_f32_32x32x16_bf16 v[82:97], v[220:223], v[110:113], 0
	v_lshl_add_u64 v[204:205], s[44:45], 0, v[140:141]
	s_mov_b64 s[6:7], 0xaf8c000
	s_add_i32 s18, s70, s8
	v_lshl_add_u64 v[206:207], v[204:205], 0, s[6:7]
	s_add_i32 m0, s18, 0xc000
	s_mov_b64 s[6:7], 0xaf8e000
	global_load_lds_dwordx4 v[206:207], off
	s_waitcnt lgkmcnt(15)
	v_mfma_f32_32x32x16_bf16 v[82:97], v[224:227], v[106:109], v[82:97]
	s_waitcnt lgkmcnt(15)
	v_mfma_f32_32x32x16_bf16 v[82:97], v[228:231], v[102:105], v[82:97]
	v_lshl_add_u64 v[204:205], v[204:205], 0, s[6:7]
	s_add_i32 m0, s18, 0xe000
	s_nop 0
	global_load_lds_dwordx4 v[204:205], off
	s_waitcnt lgkmcnt(15)
	v_mfma_f32_32x32x16_bf16 v[82:97], v[232:235], v[98:101], v[82:97]
	s_waitcnt lgkmcnt(15)
	v_mfma_f32_32x32x16_bf16 v[66:81], v[236:239], v[110:113], 0
	s_waitcnt lgkmcnt(10)
	v_mfma_f32_32x32x16_bf16 v[66:81], v[240:243], v[106:109], v[66:81]
	s_waitcnt lgkmcnt(5)
	v_mfma_f32_32x32x16_bf16 v[66:81], v[244:247], v[102:105], v[66:81]
	s_waitcnt lgkmcnt(0)
	v_mfma_f32_32x32x16_bf16 v[66:81], v[248:251], v[98:101], v[66:81]
	s_waitcnt vmcnt(2)
	s_barrier
	s_andn2_b64 vcc, exec, s[42:43]
	s_cbranch_vccz .Lfa1x_shift
.Lfa1x_shift_done:
	s_waitcnt lgkmcnt(15)
	v_mfma_f32_32x32x16_bf16 v[18:33], v[126:129], v[168:171], v[18:33]
	s_nop 4
	v_lshl_add_u64 v[204:205], s[44:45], 0, v[0:1]
	s_mov_b64 s[6:7], 0xef88000
	s_add_i32 s82, s70, s46
	v_lshl_add_u64 v[206:207], v[204:205], 0, s[6:7]
	s_mov_b32 m0, s82
	s_mov_b64 s[6:7], 0xef8a000
	global_load_lds_dwordx4 v[206:207], off
	ds_read_b64_tr_b16 v[168:169], v209 offset:8192
	ds_read_b64_tr_b16 v[170:171], v209 offset:8448
	v_exp_f32_e32 v82, v82
	v_exp_f32_e32 v83, v83
	s_waitcnt lgkmcnt(15)
	v_mfma_f32_32x32x16_bf16 v[50:65], v[126:129], v[172:175], v[50:65]
	ds_read_b64_tr_b16 v[172:173], v209 offset:8704
	ds_read_b64_tr_b16 v[174:175], v209 offset:8960
	v_add_u32_e32 v252, v208, v164
	ds_read_b128 v[220:223], v252
	v_exp_f32_e32 v84, v84
	v_exp_f32_e32 v85, v85
	v_add_f32_e32 v138, 0, v82
	v_add_f32_e32 v138, v83, v138
	s_waitcnt lgkmcnt(15)
	v_mfma_f32_32x32x16_bf16 v[34:49], v[126:129], v[176:179], v[34:49]
	v_lshl_add_u64 v[204:205], v[204:205], 0, s[6:7]
	s_add_i32 m0, s82, 0x2000
	s_nop 0
	global_load_lds_dwordx4 v[204:205], off
	ds_read_b64_tr_b16 v[176:177], v209 offset:9216
	ds_read_b64_tr_b16 v[178:179], v209 offset:9472
	v_exp_f32_e32 v86, v86
	v_exp_f32_e32 v87, v87
	v_add_f32_e32 v138, v84, v138
	v_add_f32_e32 v138, v85, v138
	s_waitcnt lgkmcnt(15)
	v_mfma_f32_32x32x16_bf16 v[2:17], v[126:129], v[180:183], v[2:17]
	ds_read_b64_tr_b16 v[180:181], v209 offset:9728
	ds_read_b64_tr_b16 v[182:183], v209 offset:9984
	v_add_u32_e32 v252, v208, v165
	ds_read_b128 v[224:227], v252
	v_exp_f32_e32 v88, v88
	v_exp_f32_e32 v89, v89
	v_add_f32_e32 v138, v86, v138
	v_add_f32_e32 v138, v87, v138
	s_waitcnt lgkmcnt(15)
	v_mfma_f32_32x32x16_bf16 v[18:33], v[122:125], v[184:187], v[18:33]
	ds_read_b64_tr_b16 v[184:185], v209 offset:12288
	ds_read_b64_tr_b16 v[186:187], v209 offset:12544
	v_exp_f32_e32 v90, v90
	v_exp_f32_e32 v91, v91
	v_add_f32_e32 v138, v88, v138
	v_add_f32_e32 v138, v89, v138
	v_cvt_pk_bf16_f32 v126, v82, v83
	s_waitcnt lgkmcnt(15)
	v_mfma_f32_32x32x16_bf16 v[50:65], v[122:125], v[188:191], v[50:65]
	ds_read_b64_tr_b16 v[188:189], v209 offset:12800
	ds_read_b64_tr_b16 v[190:191], v209 offset:13056
	v_add_u32_e32 v252, v208, v166
	ds_read_b128 v[228:231], v252
	v_exp_f32_e32 v92, v92
	v_exp_f32_e32 v93, v93
	v_add_f32_e32 v138, v90, v138
	v_add_f32_e32 v138, v91, v138
	v_cvt_pk_bf16_f32 v127, v84, v85
	s_waitcnt lgkmcnt(15)
	v_mfma_f32_32x32x16_bf16 v[34:49], v[122:125], v[192:195], v[34:49]
	ds_read_b64_tr_b16 v[192:193], v209 offset:13312
	ds_read_b64_tr_b16 v[194:195], v209 offset:13568
	v_exp_f32_e32 v94, v94
	v_exp_f32_e32 v95, v95
	v_add_f32_e32 v138, v92, v138
	v_add_f32_e32 v138, v93, v138
	v_cvt_pk_bf16_f32 v128, v86, v87
	s_waitcnt lgkmcnt(15)
	v_mfma_f32_32x32x16_bf16 v[2:17], v[122:125], v[200:203], v[2:17]
	ds_read_b64_tr_b16 v[200:201], v209 offset:13824
	ds_read_b64_tr_b16 v[202:203], v209 offset:14080
	v_add_u32_e32 v252, v208, v167
	ds_read_b128 v[232:235], v252
	v_exp_f32_e32 v96, v96
	v_exp_f32_e32 v97, v97
	v_add_f32_e32 v138, v94, v138
	v_add_f32_e32 v138, v95, v138
	v_cvt_pk_bf16_f32 v129, v88, v89
	s_waitcnt lgkmcnt(15)
	v_mfma_f32_32x32x16_bf16 v[18:33], v[118:121], v[168:171], v[18:33]
	ds_read_b64_tr_b16 v[168:169], v210 offset:0
	ds_read_b64_tr_b16 v[170:171], v210 offset:256
	v_exp_f32_e32 v66, v66
	v_exp_f32_e32 v67, v67
	v_add_f32_e32 v138, v96, v138
	v_add_f32_e32 v138, v97, v138
	v_cvt_pk_bf16_f32 v122, v90, v91
	s_waitcnt lgkmcnt(15)
	v_mfma_f32_32x32x16_bf16 v[50:65], v[118:121], v[172:175], v[50:65]
	ds_read_b64_tr_b16 v[172:173], v210 offset:512
	ds_read_b64_tr_b16 v[174:175], v210 offset:768
	v_add_u32_e32 v252, v208, v164
	ds_read_b128 v[236:239], v252 offset:8192
	v_exp_f32_e32 v68, v68
	v_exp_f32_e32 v69, v69
	v_add_f32_e32 v138, v66, v138
	v_add_f32_e32 v138, v67, v138
	v_cvt_pk_bf16_f32 v123, v92, v93
	s_waitcnt lgkmcnt(15)
	v_mfma_f32_32x32x16_bf16 v[34:49], v[118:121], v[176:179], v[34:49]
	ds_read_b64_tr_b16 v[176:177], v210 offset:1024
	ds_read_b64_tr_b16 v[178:179], v210 offset:1280
	v_exp_f32_e32 v70, v70
	v_exp_f32_e32 v71, v71
	v_add_f32_e32 v138, v68, v138
	v_add_f32_e32 v138, v69, v138
	v_cvt_pk_bf16_f32 v124, v94, v95
	s_waitcnt lgkmcnt(15)
	v_mfma_f32_32x32x16_bf16 v[2:17], v[118:121], v[180:183], v[2:17]
	ds_read_b64_tr_b16 v[180:181], v210 offset:1536
	ds_read_b64_tr_b16 v[182:183], v210 offset:1792
	v_add_u32_e32 v252, v208, v165
	ds_read_b128 v[240:243], v252 offset:8192
	v_exp_f32_e32 v72, v72
	v_exp_f32_e32 v73, v73
	v_add_f32_e32 v138, v70, v138
	v_add_f32_e32 v138, v71, v138
	v_cvt_pk_bf16_f32 v125, v96, v97
	s_waitcnt lgkmcnt(15)
	v_mfma_f32_32x32x16_bf16 v[18:33], v[114:117], v[184:187], v[18:33]
	ds_read_b64_tr_b16 v[184:185], v210 offset:4096
	ds_read_b64_tr_b16 v[186:187], v210 offset:4352
	v_exp_f32_e32 v74, v74
	v_exp_f32_e32 v75, v75
	v_add_f32_e32 v138, v72, v138
	v_add_f32_e32 v138, v73, v138
	v_cvt_pk_bf16_f32 v118, v66, v67
	s_waitcnt lgkmcnt(15)
	v_mfma_f32_32x32x16_bf16 v[50:65], v[114:117], v[188:191], v[50:65]
	ds_read_b64_tr_b16 v[188:189], v210 offset:4608
	ds_read_b64_tr_b16 v[190:191], v210 offset:4864
	v_add_u32_e32 v252, v208, v166
	ds_read_b128 v[244:247], v252 offset:8192
	v_exp_f32_e32 v76, v76
	v_exp_f32_e32 v77, v77
	v_add_f32_e32 v138, v74, v138
	v_add_f32_e32 v138, v75, v138
	v_cvt_pk_bf16_f32 v119, v68, v69
	s_waitcnt lgkmcnt(15)
	v_mfma_f32_32x32x16_bf16 v[34:49], v[114:117], v[192:195], v[34:49]
	ds_read_b64_tr_b16 v[192:193], v210 offset:5120
	ds_read_b64_tr_b16 v[194:195], v210 offset:5376
	v_exp_f32_e32 v78, v78
	v_exp_f32_e32 v79, v79
	v_add_f32_e32 v138, v76, v138
	v_add_f32_e32 v138, v77, v138
	v_cvt_pk_bf16_f32 v120, v70, v71
	s_waitcnt lgkmcnt(15)
	v_mfma_f32_32x32x16_bf16 v[2:17], v[114:117], v[200:203], v[2:17]
	ds_read_b64_tr_b16 v[200:201], v210 offset:5632
	ds_read_b64_tr_b16 v[202:203], v210 offset:5888
	v_add_u32_e32 v252, v208, v167
	ds_read_b128 v[248:251], v252 offset:8192
	v_exp_f32_e32 v80, v80
	v_exp_f32_e32 v81, v81
	v_add_f32_e32 v138, v78, v138
	v_add_f32_e32 v138, v79, v138
	v_cvt_pk_bf16_f32 v121, v72, v73
	v_add_f32_e32 v138, v80, v138
	v_add_f32_e32 v138, v81, v138
	v_cvt_pk_bf16_f32 v114, v74, v75
	v_cvt_pk_bf16_f32 v115, v76, v77
	v_cvt_pk_bf16_f32 v116, v78, v79
	v_cvt_pk_bf16_f32 v117, v80, v81
	s_nop 0
	v_cmp_ge_f32_e32 vcc, s66, v138
	s_cmp_eq_u64 vcc, exec
	s_cbranch_scc0 .Lfa1x_slow
	v_add_f32_e32 v163, v163, v138
.Lfa1x_slow_done:
	s_add_u32 s44, s44, 0x4000
	s_addc_u32 s45, s45, 0
	s_add_i32 s87, s87, 64
	s_mov_b32 s6, s83
	s_mov_b32 s83, s84
	s_mov_b32 s84, s33
	s_add_i32 s10, s86, s87
	s_abs_i32 s11, s10
	s_cmpk_lt_i32 s11, 0xda
	s_cbranch_scc1 .Lfa1x_exit
	s_add_i32 s11, s87, 64
	s_cmpk_eq_i32 s11, 0x1f40
	s_cbranch_scc0 .Lfa1x_loop

.Lfa1x_slow:
	v_max_f32_e32 v252, v82, v83
	v_max3_f32 v252, v252, v84, v85
	v_max3_f32 v252, v252, v86, v87
	v_max3_f32 v252, v252, v88, v89
	v_max3_f32 v252, v252, v90, v91
	v_max3_f32 v252, v252, v92, v93
	v_max3_f32 v252, v252, v94, v95
	v_max3_f32 v252, v252, v96, v97
	v_max3_f32 v252, v252, v66, v67
	v_max3_f32 v252, v252, v68, v69
	v_max3_f32 v252, v252, v70, v71
	v_max3_f32 v252, v252, v72, v73
	v_max3_f32 v252, v252, v74, v75
	v_max3_f32 v252, v252, v76, v77
	v_max3_f32 v252, v252, v78, v79
	v_max3_f32 v252, v252, v80, v81
	v_mov_b32_e32 v253, v252
	s_nop 1
	v_permlane32_swap_b32_e32 v252, v253
	v_max_f32_e32 v252, v252, v253
	v_log_f32_e32 v253, v252
	v_cmp_lt_f32_e64 s[6:7], s66, v252
	s_mov_b64 s[42:43], -1
	s_nop 0
	v_cndmask_b32_e64 v253, 0, v253, s[6:7]
	v_exp_f32_e64 v139, -v253
	v_add_f32_e32 v162, v162, v253
	s_nop 0
	v_mul_f32_e32 v82, v82, v139
	v_mul_f32_e32 v83, v83, v139
	v_mul_f32_e32 v84, v84, v139
	v_mul_f32_e32 v85, v85, v139
	v_mul_f32_e32 v86, v86, v139
	v_mul_f32_e32 v87, v87, v139
	v_mul_f32_e32 v88, v88, v139
	v_mul_f32_e32 v89, v89, v139
	v_mul_f32_e32 v90, v90, v139
	v_mul_f32_e32 v91, v91, v139
	v_mul_f32_e32 v92, v92, v139
	v_mul_f32_e32 v93, v93, v139
	v_mul_f32_e32 v94, v94, v139
	v_mul_f32_e32 v95, v95, v139
	v_mul_f32_e32 v96, v96, v139
	v_mul_f32_e32 v97, v97, v139
	v_mul_f32_e32 v66, v66, v139
	v_mul_f32_e32 v67, v67, v139
	v_mul_f32_e32 v68, v68, v139
	v_mul_f32_e32 v69, v69, v139
	v_mul_f32_e32 v70, v70, v139
	v_mul_f32_e32 v71, v71, v139
	v_mul_f32_e32 v72, v72, v139
	v_mul_f32_e32 v73, v73, v139
	v_mul_f32_e32 v74, v74, v139
	v_mul_f32_e32 v75, v75, v139
	v_mul_f32_e32 v76, v76, v139
	v_mul_f32_e32 v77, v77, v139
	v_mul_f32_e32 v78, v78, v139
	v_mul_f32_e32 v79, v79, v139
	v_mul_f32_e32 v80, v80, v139
	v_mul_f32_e32 v81, v81, v139
	v_mul_f32_e32 v138, v138, v139
	v_cvt_pk_bf16_f32 v126, v82, v83
	v_cvt_pk_bf16_f32 v127, v84, v85
	v_cvt_pk_bf16_f32 v128, v86, v87
	v_cvt_pk_bf16_f32 v129, v88, v89
	v_cvt_pk_bf16_f32 v122, v90, v91
	v_cvt_pk_bf16_f32 v123, v92, v93
	v_cvt_pk_bf16_f32 v124, v94, v95
	v_cvt_pk_bf16_f32 v125, v96, v97
	v_cvt_pk_bf16_f32 v118, v66, v67
	v_cvt_pk_bf16_f32 v119, v68, v69
	v_cvt_pk_bf16_f32 v120, v70, v71
	v_cvt_pk_bf16_f32 v121, v72, v73
	v_cvt_pk_bf16_f32 v114, v74, v75
	v_cvt_pk_bf16_f32 v115, v76, v77
	v_cvt_pk_bf16_f32 v116, v78, v79
	v_cvt_pk_bf16_f32 v117, v80, v81
	v_fmac_f32_e32 v138, v163, v139
	v_mov_b32_e32 v163, v138
	s_and_saveexec_b64 s[6:7], s[4:5]
	ds_write_b32 v160, v139 offset:128
	s_or_b64 exec, exec, s[6:7]
	s_waitcnt lgkmcnt(0)
	v_add_u32_e32 v252, s71, v130
	ds_read_b128 v[82:85], v252 offset:224
	ds_read_b128 v[86:89], v252 offset:192
	ds_read_b128 v[90:93], v252 offset:160
	ds_read_b128 v[94:97], v252 offset:128
	s_waitcnt lgkmcnt(0)
	v_mul_f32_e32 v30, v30, v82
	v_mul_f32_e32 v31, v31, v83
	v_mul_f32_e32 v32, v32, v84
	v_mul_f32_e32 v33, v33, v85
	v_mul_f32_e32 v26, v26, v86
	v_mul_f32_e32 v27, v27, v87
	v_mul_f32_e32 v28, v28, v88
	v_mul_f32_e32 v29, v29, v89
	v_mul_f32_e32 v22, v22, v90
	v_mul_f32_e32 v23, v23, v91
	v_mul_f32_e32 v24, v24, v92
	v_mul_f32_e32 v25, v25, v93
	v_mul_f32_e32 v18, v18, v94
	v_mul_f32_e32 v19, v19, v95
	v_mul_f32_e32 v20, v20, v96
	v_mul_f32_e32 v21, v21, v97
	v_mul_f32_e32 v62, v62, v82
	v_mul_f32_e32 v63, v63, v83
	v_mul_f32_e32 v64, v64, v84
	v_mul_f32_e32 v65, v65, v85
	v_mul_f32_e32 v58, v58, v86
	v_mul_f32_e32 v59, v59, v87
	v_mul_f32_e32 v60, v60, v88
	v_mul_f32_e32 v61, v61, v89
	v_mul_f32_e32 v54, v54, v90
	v_mul_f32_e32 v55, v55, v91
	v_mul_f32_e32 v56, v56, v92
	v_mul_f32_e32 v57, v57, v93
	v_mul_f32_e32 v50, v50, v94
	v_mul_f32_e32 v51, v51, v95
	v_mul_f32_e32 v52, v52, v96
	v_mul_f32_e32 v53, v53, v97
	v_mul_f32_e32 v46, v46, v82
	v_mul_f32_e32 v47, v47, v83
	v_mul_f32_e32 v48, v48, v84
	v_mul_f32_e32 v49, v49, v85
	v_mul_f32_e32 v42, v42, v86
	v_mul_f32_e32 v43, v43, v87
	v_mul_f32_e32 v44, v44, v88
	v_mul_f32_e32 v45, v45, v89
	v_mul_f32_e32 v38, v38, v90
	v_mul_f32_e32 v39, v39, v91
	v_mul_f32_e32 v40, v40, v92
	v_mul_f32_e32 v41, v41, v93
	v_mul_f32_e32 v34, v34, v94
	v_mul_f32_e32 v35, v35, v95
	v_mul_f32_e32 v36, v36, v96
	v_mul_f32_e32 v37, v37, v97
	v_mul_f32_e32 v14, v14, v82
	v_mul_f32_e32 v15, v15, v83
	v_mul_f32_e32 v16, v16, v84
	v_mul_f32_e32 v17, v17, v85
	v_mul_f32_e32 v10, v10, v86
	v_mul_f32_e32 v11, v11, v87
	v_mul_f32_e32 v12, v12, v88
	v_mul_f32_e32 v13, v13, v89
	v_mul_f32_e32 v6, v6, v90
	v_mul_f32_e32 v7, v7, v91
	v_mul_f32_e32 v8, v8, v92
	v_mul_f32_e32 v9, v9, v93
	v_mul_f32_e32 v2, v2, v94
	v_mul_f32_e32 v3, v3, v95
	v_mul_f32_e32 v4, v4, v96
	v_mul_f32_e32 v5, v5, v97
	s_branch .Lfa1x_slow_done
